# FF1 epilogue: canonicalising v_max before the ReLU clamp removed (93 VALU per tile per wave)
# baseline (speedup 1.0000x reference)
.LBB0_83:
	v_mov_b32_e32 v64, v203
	s_lshl_b32 s2, s92, 8
	s_add_i32 s2, s2, s57
	s_lshl_b32 s3, s62, 8
	v_and_or_b32 v130, v64, 15, s2
	v_lshrrev_b32_e32 v64, 1, v64
	v_and_or_b32 v64, v64, 24, s3
	v_or_b32_e32 v138, s58, v64
	v_max_f32_e32 v126, 0, v126
	v_max_f32_e32 v122, 0, v122
	v_max_f32_e32 v127, 0, v127
	v_max_f32_e32 v123, 0, v123
	v_max_f32_e32 v128, 0, v128
	v_max_f32_e32 v124, 0, v124
	v_max_f32_e32 v129, 0, v129
	v_max_f32_e32 v125, 0, v125
	v_max_f32_e32 v118, 0, v118
	v_ashrrev_i32_e32 v131, 31, v130
	v_max_f32_e32 v114, 0, v114
	v_lshlrev_b64 v[140:141], 13, v[130:131]
	v_pk_mul_f32 v[126:127], v[126:127], v[126:127]
	v_pk_mul_f32 v[122:123], v[122:123], v[122:123]
	v_pk_mul_f32 v[128:129], v[128:129], v[128:129]
	v_ashrrev_i32_e32 v139, 31, v138
	v_max_f32_e32 v119, 0, v119
	v_pk_mul_f32 v[142:143], v[124:125], v[124:125]
	v_cvt_pk_bf16_f32 v124, v126, v127
	v_cvt_pk_bf16_f32 v125, v128, v129
	v_cvt_pk_bf16_f32 v126, v122, v123
	v_lshl_add_u64 v[128:129], s[46:47], 0, v[140:141]
	v_lshlrev_b64 v[122:123], 1, v[138:139]
	v_max_f32_e32 v115, 0, v115
	v_cvt_pk_bf16_f32 v127, v142, v143
	v_lshl_add_u64 v[128:129], v[128:129], 0, v[122:123]
	v_max_f32_e32 v64, v120, v120
	global_store_dwordx4 v[128:129], v[124:127], off
	v_pk_mul_f32 v[118:119], v[118:119], v[118:119]
	v_max_f32_e32 v56, v56, v56
	v_pk_mul_f32 v[124:125], v[114:115], v[114:115]
	v_max_f32_e32 v114, 0, v64
	v_max_f32_e32 v116, 0, v116
	v_max_f32_e32 v115, 0, v121
	v_max_f32_e32 v117, 0, v117
	v_max_f32_e32 v110, 0, v110
	v_max_f32_e32 v106, 0, v106
	v_max_f32_e32 v111, 0, v111
	v_pk_mul_f32 v[120:121], v[114:115], v[114:115]
	v_pk_mul_f32 v[126:127], v[116:117], v[116:117]
	v_max_f32_e32 v107, 0, v107
	v_cvt_pk_bf16_f32 v114, v118, v119
	v_cvt_pk_bf16_f32 v115, v120, v121
	v_cvt_pk_bf16_f32 v116, v124, v125
	v_cvt_pk_bf16_f32 v117, v126, v127
	v_max_f32_e32 v64, v112, v112
	global_store_dwordx4 v[128:129], v[114:117], off offset:256
	v_pk_mul_f32 v[110:111], v[110:111], v[110:111]
	v_max_f32_e32 v57, v57, v57
	v_pk_mul_f32 v[116:117], v[106:107], v[106:107]
	v_max_f32_e32 v106, 0, v64
	v_max_f32_e32 v108, 0, v108
	v_max_f32_e32 v107, 0, v113
	v_max_f32_e32 v109, 0, v109
	v_or_b32_e32 v114, 16, v130
	v_max_f32_e32 v102, 0, v102
	v_ashrrev_i32_e32 v115, 31, v114
	v_max_f32_e32 v98, 0, v98
	v_lshlrev_b64 v[114:115], 13, v[114:115]
	v_max_f32_e32 v103, 0, v103
	v_pk_mul_f32 v[112:113], v[106:107], v[106:107]
	v_pk_mul_f32 v[118:119], v[108:109], v[108:109]
	v_cvt_pk_bf16_f32 v106, v110, v111
	v_lshl_add_u64 v[110:111], s[46:47], 0, v[114:115]
	v_max_f32_e32 v99, 0, v99
	v_cvt_pk_bf16_f32 v107, v112, v113
	v_cvt_pk_bf16_f32 v108, v116, v117
	v_cvt_pk_bf16_f32 v109, v118, v119
	v_lshl_add_u64 v[110:111], v[110:111], 0, v[122:123]
	v_max_f32_e32 v64, v104, v104
	global_store_dwordx4 v[110:111], v[106:109], off
	v_pk_mul_f32 v[102:103], v[102:103], v[102:103]
	v_max_f32_e32 v56, 0, v56
	v_pk_mul_f32 v[106:107], v[98:99], v[98:99]
	v_max_f32_e32 v98, 0, v64
	v_max_f32_e32 v100, 0, v100
	v_max_f32_e32 v99, 0, v105
	v_max_f32_e32 v101, 0, v101
	v_max_f32_e32 v94, 0, v94
	v_max_f32_e32 v90, 0, v90
	v_max_f32_e32 v95, 0, v95
	v_pk_mul_f32 v[104:105], v[98:99], v[98:99]
	v_pk_mul_f32 v[108:109], v[100:101], v[100:101]
	v_max_f32_e32 v91, 0, v91
	v_cvt_pk_bf16_f32 v98, v102, v103
	v_cvt_pk_bf16_f32 v99, v104, v105
	v_cvt_pk_bf16_f32 v100, v106, v107
	v_cvt_pk_bf16_f32 v101, v108, v109
	v_max_f32_e32 v64, v96, v96
	global_store_dwordx4 v[110:111], v[98:101], off offset:256
	v_pk_mul_f32 v[94:95], v[94:95], v[94:95]
	v_max_f32_e32 v57, 0, v57
	v_pk_mul_f32 v[100:101], v[90:91], v[90:91]
	v_max_f32_e32 v90, 0, v64
	v_max_f32_e32 v92, 0, v92
	v_max_f32_e32 v91, 0, v97
	v_max_f32_e32 v93, 0, v93
	v_or_b32_e32 v98, 32, v130
	v_max_f32_e32 v86, 0, v86
	v_ashrrev_i32_e32 v99, 31, v98
	v_max_f32_e32 v82, 0, v82
	v_lshlrev_b64 v[98:99], 13, v[98:99]
	v_max_f32_e32 v87, 0, v87
	v_pk_mul_f32 v[96:97], v[90:91], v[90:91]
	v_pk_mul_f32 v[102:103], v[92:93], v[92:93]
	v_cvt_pk_bf16_f32 v90, v94, v95
	v_lshl_add_u64 v[94:95], s[46:47], 0, v[98:99]
	v_max_f32_e32 v83, 0, v83
	v_cvt_pk_bf16_f32 v91, v96, v97
	v_cvt_pk_bf16_f32 v92, v100, v101
	v_cvt_pk_bf16_f32 v93, v102, v103
	v_lshl_add_u64 v[94:95], v[94:95], 0, v[122:123]
	v_max_f32_e32 v64, v88, v88
	global_store_dwordx4 v[94:95], v[90:93], off
	v_pk_mul_f32 v[86:87], v[86:87], v[86:87]
	v_max_f32_e32 v60, v60, v60
	v_pk_mul_f32 v[90:91], v[82:83], v[82:83]
	v_max_f32_e32 v82, 0, v64
	v_max_f32_e32 v84, 0, v84
	v_max_f32_e32 v83, 0, v89
	v_max_f32_e32 v85, 0, v85
	v_max_f32_e32 v78, 0, v78
	v_max_f32_e32 v74, 0, v74
	v_max_f32_e32 v79, 0, v79
	v_pk_mul_f32 v[88:89], v[82:83], v[82:83]
	v_pk_mul_f32 v[92:93], v[84:85], v[84:85]
	v_max_f32_e32 v75, 0, v75
	v_cvt_pk_bf16_f32 v82, v86, v87
	v_cvt_pk_bf16_f32 v83, v88, v89
	v_cvt_pk_bf16_f32 v84, v90, v91
	v_cvt_pk_bf16_f32 v85, v92, v93
	v_max_f32_e32 v64, v80, v80
	global_store_dwordx4 v[94:95], v[82:85], off offset:256
	v_pk_mul_f32 v[78:79], v[78:79], v[78:79]
	v_max_f32_e32 v61, v61, v61
	v_pk_mul_f32 v[84:85], v[74:75], v[74:75]
	v_max_f32_e32 v74, 0, v64
	v_max_f32_e32 v76, 0, v76
	v_max_f32_e32 v75, 0, v81
	v_max_f32_e32 v77, 0, v77
	v_or_b32_e32 v82, 48, v130
	v_max_f32_e32 v70, 0, v70
	v_ashrrev_i32_e32 v83, 31, v82
	v_max_f32_e32 v66, 0, v66
	v_lshlrev_b64 v[82:83], 13, v[82:83]
	v_max_f32_e32 v71, 0, v71
	v_pk_mul_f32 v[80:81], v[74:75], v[74:75]
	v_pk_mul_f32 v[86:87], v[76:77], v[76:77]
	v_cvt_pk_bf16_f32 v74, v78, v79
	v_lshl_add_u64 v[78:79], s[46:47], 0, v[82:83]
	v_max_f32_e32 v67, 0, v67
	v_cvt_pk_bf16_f32 v75, v80, v81
	v_cvt_pk_bf16_f32 v76, v84, v85
	v_cvt_pk_bf16_f32 v77, v86, v87
	v_lshl_add_u64 v[78:79], v[78:79], 0, v[122:123]
	v_max_f32_e32 v64, v72, v72
	global_store_dwordx4 v[78:79], v[74:77], off
	v_pk_mul_f32 v[70:71], v[70:71], v[70:71]
	v_max_f32_e32 v60, 0, v60
	v_pk_mul_f32 v[74:75], v[66:67], v[66:67]
	v_max_f32_e32 v66, 0, v64
	v_max_f32_e32 v68, 0, v68
	v_max_f32_e32 v67, 0, v73
	v_max_f32_e32 v69, 0, v69
	v_pk_mul_f32 v[72:73], v[66:67], v[66:67]
	v_pk_mul_f32 v[76:77], v[68:69], v[68:69]
	v_cvt_pk_bf16_f32 v66, v70, v71
	v_cvt_pk_bf16_f32 v67, v72, v73
	v_cvt_pk_bf16_f32 v68, v74, v75
	v_cvt_pk_bf16_f32 v69, v76, v77
	global_store_dwordx4 v[78:79], v[66:69], off offset:256
	v_max_f32_e32 v61, 0, v61
	s_nop 0
	v_add_u32_e32 v66, 0x80, v130
	v_pk_mul_f32 v[68:69], v[56:57], v[56:57]
	v_max_f32_e32 v57, v58, v58
	v_ashrrev_i32_e32 v67, 31, v66
	v_max_f32_e32 v56, v62, v62
	v_max_f32_e32 v58, 0, v57
	v_max_f32_e32 v57, v63, v63
	v_lshlrev_b64 v[66:67], 13, v[66:67]
	v_pk_mul_f32 v[60:61], v[60:61], v[60:61]
	v_max_f32_e32 v56, 0, v56
	v_max_f32_e32 v57, 0, v57
	v_max_f32_e32 v59, 0, v59
	v_pk_mul_f32 v[62:63], v[56:57], v[56:57]
	v_pk_mul_f32 v[70:71], v[58:59], v[58:59]
	v_cvt_pk_bf16_f32 v56, v60, v61
	v_lshl_add_u64 v[60:61], s[46:47], 0, v[66:67]
	v_cvt_pk_bf16_f32 v57, v62, v63
	v_cvt_pk_bf16_f32 v58, v68, v69
	v_cvt_pk_bf16_f32 v59, v70, v71
	v_lshl_add_u64 v[60:61], v[60:61], 0, v[122:123]
	v_max_f32_e32 v48, 0, v48
	v_max_f32_e32 v49, 0, v49
	global_store_dwordx4 v[60:61], v[56:59], off
	s_nop 0
	s_nop 0
	v_pk_mul_f32 v[56:57], v[48:49], v[48:49]
	v_max_f32_e32 v49, v50, v50
	v_max_f32_e32 v48, v54, v54
	v_max_f32_e32 v50, 0, v49
	v_max_f32_e32 v49, v55, v55
	v_max_f32_e32 v52, 0, v52
	v_max_f32_e32 v53, 0, v53
	v_max_f32_e32 v48, 0, v48
	v_max_f32_e32 v49, 0, v49
	v_max_f32_e32 v51, 0, v51
	v_pk_mul_f32 v[52:53], v[52:53], v[52:53]
	v_pk_mul_f32 v[54:55], v[48:49], v[48:49]
	v_pk_mul_f32 v[58:59], v[50:51], v[50:51]
	v_cvt_pk_bf16_f32 v48, v52, v53
	v_cvt_pk_bf16_f32 v49, v54, v55
	v_cvt_pk_bf16_f32 v50, v56, v57
	v_cvt_pk_bf16_f32 v51, v58, v59
	v_max_f32_e32 v40, 0, v40
	v_max_f32_e32 v41, 0, v41
	global_store_dwordx4 v[60:61], v[48:51], off offset:256
	s_nop 0
	s_nop 0
	v_add_u32_e32 v48, 0x90, v130
	v_pk_mul_f32 v[50:51], v[40:41], v[40:41]
	v_max_f32_e32 v41, v42, v42
	v_ashrrev_i32_e32 v49, 31, v48
	v_max_f32_e32 v44, 0, v44
	v_max_f32_e32 v45, 0, v45
	v_max_f32_e32 v40, v46, v46
	v_max_f32_e32 v42, 0, v41
	v_max_f32_e32 v41, v47, v47
	v_lshlrev_b64 v[48:49], 13, v[48:49]
	v_pk_mul_f32 v[44:45], v[44:45], v[44:45]
	v_max_f32_e32 v40, 0, v40
	v_max_f32_e32 v41, 0, v41
	v_max_f32_e32 v43, 0, v43
	v_pk_mul_f32 v[46:47], v[40:41], v[40:41]
	v_pk_mul_f32 v[52:53], v[42:43], v[42:43]
	v_cvt_pk_bf16_f32 v40, v44, v45
	v_lshl_add_u64 v[44:45], s[46:47], 0, v[48:49]
	v_cvt_pk_bf16_f32 v41, v46, v47
	v_cvt_pk_bf16_f32 v42, v50, v51
	v_cvt_pk_bf16_f32 v43, v52, v53
	v_lshl_add_u64 v[44:45], v[44:45], 0, v[122:123]
	v_max_f32_e32 v32, 0, v32
	v_max_f32_e32 v33, 0, v33
	global_store_dwordx4 v[44:45], v[40:43], off
	s_nop 0
	s_nop 0
	v_pk_mul_f32 v[40:41], v[32:33], v[32:33]
	v_max_f32_e32 v33, v34, v34
	v_max_f32_e32 v32, v38, v38
	v_max_f32_e32 v34, 0, v33
	v_max_f32_e32 v33, v39, v39
	v_max_f32_e32 v36, 0, v36
	v_max_f32_e32 v37, 0, v37
	v_max_f32_e32 v32, 0, v32
	v_max_f32_e32 v33, 0, v33
	v_max_f32_e32 v35, 0, v35
	v_pk_mul_f32 v[36:37], v[36:37], v[36:37]
	v_pk_mul_f32 v[38:39], v[32:33], v[32:33]
	v_pk_mul_f32 v[42:43], v[34:35], v[34:35]
	v_cvt_pk_bf16_f32 v32, v36, v37
	v_cvt_pk_bf16_f32 v33, v38, v39
	v_cvt_pk_bf16_f32 v34, v40, v41
	v_cvt_pk_bf16_f32 v35, v42, v43
	v_max_f32_e32 v24, 0, v24
	v_max_f32_e32 v25, 0, v25
	global_store_dwordx4 v[44:45], v[32:35], off offset:256
	s_nop 0
	s_nop 0
	v_add_u32_e32 v32, 0xa0, v130
	v_pk_mul_f32 v[34:35], v[24:25], v[24:25]
	v_max_f32_e32 v25, v26, v26
	v_ashrrev_i32_e32 v33, 31, v32
	v_max_f32_e32 v28, 0, v28
	v_max_f32_e32 v29, 0, v29
	v_max_f32_e32 v24, v30, v30
	v_max_f32_e32 v26, 0, v25
	v_max_f32_e32 v25, v31, v31
	v_lshlrev_b64 v[32:33], 13, v[32:33]
	v_pk_mul_f32 v[28:29], v[28:29], v[28:29]
	v_max_f32_e32 v24, 0, v24
	v_max_f32_e32 v25, 0, v25
	v_max_f32_e32 v27, 0, v27
	v_pk_mul_f32 v[30:31], v[24:25], v[24:25]
	v_pk_mul_f32 v[36:37], v[26:27], v[26:27]
	v_cvt_pk_bf16_f32 v24, v28, v29
	v_lshl_add_u64 v[28:29], s[46:47], 0, v[32:33]
	v_cvt_pk_bf16_f32 v25, v30, v31
	v_cvt_pk_bf16_f32 v26, v34, v35
	v_cvt_pk_bf16_f32 v27, v36, v37
	v_lshl_add_u64 v[28:29], v[28:29], 0, v[122:123]
	v_max_f32_e32 v16, 0, v16
	v_max_f32_e32 v17, 0, v17
	global_store_dwordx4 v[28:29], v[24:27], off
	s_nop 0
	s_nop 0
	v_pk_mul_f32 v[24:25], v[16:17], v[16:17]
	v_max_f32_e32 v17, v18, v18
	v_max_f32_e32 v16, v22, v22
	v_max_f32_e32 v18, 0, v17
	v_max_f32_e32 v17, v23, v23
	v_max_f32_e32 v20, 0, v20
	v_max_f32_e32 v21, 0, v21
	v_max_f32_e32 v16, 0, v16
	v_max_f32_e32 v17, 0, v17
	v_max_f32_e32 v19, 0, v19
	v_pk_mul_f32 v[20:21], v[20:21], v[20:21]
	v_pk_mul_f32 v[22:23], v[16:17], v[16:17]
	v_pk_mul_f32 v[26:27], v[18:19], v[18:19]
	v_cvt_pk_bf16_f32 v16, v20, v21
	v_cvt_pk_bf16_f32 v17, v22, v23
	v_cvt_pk_bf16_f32 v18, v24, v25
	v_cvt_pk_bf16_f32 v19, v26, v27
	v_max_f32_e32 v8, 0, v8
	v_max_f32_e32 v9, 0, v9
	global_store_dwordx4 v[28:29], v[16:19], off offset:256
	s_nop 0
	s_nop 0
	v_add_u32_e32 v16, 0xb0, v130
	v_pk_mul_f32 v[18:19], v[8:9], v[8:9]
	v_max_f32_e32 v9, v10, v10
	v_ashrrev_i32_e32 v17, 31, v16
	v_max_f32_e32 v12, 0, v12
	v_max_f32_e32 v13, 0, v13
	v_max_f32_e32 v8, v14, v14
	v_max_f32_e32 v10, 0, v9
	v_max_f32_e32 v9, v15, v15
	v_lshlrev_b64 v[16:17], 13, v[16:17]
	v_pk_mul_f32 v[12:13], v[12:13], v[12:13]
	v_max_f32_e32 v8, 0, v8
	v_max_f32_e32 v9, 0, v9
	v_max_f32_e32 v11, 0, v11
	v_pk_mul_f32 v[14:15], v[8:9], v[8:9]
	v_pk_mul_f32 v[20:21], v[10:11], v[10:11]
	v_cvt_pk_bf16_f32 v8, v12, v13
	v_lshl_add_u64 v[12:13], s[46:47], 0, v[16:17]
	v_cvt_pk_bf16_f32 v9, v14, v15
	v_cvt_pk_bf16_f32 v10, v18, v19
	v_cvt_pk_bf16_f32 v11, v20, v21
	v_lshl_add_u64 v[12:13], v[12:13], 0, v[122:123]
	v_max_f32_e32 v0, 0, v0
	v_max_f32_e32 v1, 0, v1
	global_store_dwordx4 v[12:13], v[8:11], off
	s_nop 0
	s_nop 0
	v_pk_mul_f32 v[8:9], v[0:1], v[0:1]
	v_max_f32_e32 v1, v2, v2
	v_max_f32_e32 v0, v6, v6
	v_max_f32_e32 v2, 0, v1
	v_max_f32_e32 v1, v7, v7
	v_max_f32_e32 v4, 0, v4
	v_max_f32_e32 v5, 0, v5
	v_max_f32_e32 v0, 0, v0
	v_max_f32_e32 v1, 0, v1
	v_max_f32_e32 v3, 0, v3
	v_pk_mul_f32 v[4:5], v[4:5], v[4:5]
	v_pk_mul_f32 v[6:7], v[0:1], v[0:1]
	v_pk_mul_f32 v[10:11], v[2:3], v[2:3]
	v_cvt_pk_bf16_f32 v0, v4, v5
	v_cvt_pk_bf16_f32 v1, v6, v7
	v_cvt_pk_bf16_f32 v2, v8, v9
	v_cvt_pk_bf16_f32 v3, v10, v11
	s_andn2_b64 vcc, exec, s[82:83]
	s_mov_b64 s[2:3], -1
	v_readlane_b32 s71, v254, 49
	global_store_dwordx4 v[12:13], v[0:3], off offset:256
	s_cbranch_vccnz .LBB0_76
	s_andn2_b64 vcc, exec, s[40:41]
	s_cbranch_vccnz .LBB0_75
	s_barrier
	s_branch .LBB0_75
